# prompt attention: straight-line softmax for the six K tiles whose position bias is one clamped value (max over raw scores, folded fma+exp2 in place, packed f32 sums; no op_sel broadcasts)
# speedup vs baseline: 1.0018x; 1.0018x over previous
.LBB0_1429:
	v_mov_b32_e32 v4, v252
	s_waitcnt vmcnt(63) expcnt(7) lgkmcnt(15)
	v_readfirstlane_b32 s4, v4
	s_barrier
	s_load_dwordx2 s[2:3], s[0:1], 0x40
	s_ashr_i32 s10, s4, 6
	v_and_b32_e32 v173, 63, v4
	s_mul_i32 s6, s10, 0x101
	s_mul_i32 s5, s10, 0x410
	v_add_u32_e32 v2, s6, v173
	s_add_i32 s8, s5, 0
	v_ashrrev_i32_e32 v3, 31, v2
	v_or_b32_e32 v0, 0xffffffc0, v173
	v_lshl_add_u32 v5, v173, 2, s8
	s_waitcnt lgkmcnt(0)
	v_lshl_add_u64 v[2:3], v[2:3], 2, s[2:3]
	s_mov_b64 s[2:3], 0
	global_load_dword v243, v[2:3], off
	global_load_dword v248, v[2:3], off offset:256
	global_load_dword v249, v[2:3], off offset:512
	global_load_dword v250, v[2:3], off offset:768
	v_cmp_eq_u32_e32 vcc, 0xffffffc0, v0
	s_and_saveexec_b64 s[2:3], vcc
	global_load_dword v251, v[2:3], off offset:1024
	s_waitcnt vmcnt(0)
	v_mul_f32_e32 v251, 0x3fb8aa3b, v251
	ds_write_b32 v5, v251 offset:1024
	s_or_b64 exec, exec, s[2:3]
	v_mul_f32_e32 v243, 0x3fb8aa3b, v243
	v_mul_f32_e32 v248, 0x3fb8aa3b, v248
	v_mul_f32_e32 v249, 0x3fb8aa3b, v249
	v_mul_f32_e32 v250, 0x3fb8aa3b, v250
	ds_write_b32 v5, v243
	ds_write_b32 v5, v248 offset:256
	ds_write_b32 v5, v249 offset:512
	ds_write_b32 v5, v250 offset:768
	s_add_i32 s11, s18, 0xffb9
	s_and_b32 s9, s11, 0xffff
	s_mul_i32 s2, s9, 0x8889
	s_lshr_b32 s2, s2, 22
	s_lshl_b32 s3, s2, 7
	s_mulk_i32 s2, 0x78
	s_sub_i32 s2, s11, s2
	s_add_i32 s2, s2, 8
	s_and_b32 s2, s2, 0xffff
	s_add_i32 s33, s3, s2
	s_lshr_b32 s2, s33, 7
	s_lshl_b32 s76, s2, 22
	s_lshl_b32 s2, s2, 3
	s_and_b32 s6, s4, 0xffffffc0
	s_add_i32 s2, s10, s2
	s_ashr_i32 s7, s6, 31
	s_ashr_i32 s3, s2, 31
	s_lshl_b64 s[2:3], s[2:3], 20
	s_lshl_b64 s[4:5], s[6:7], 1
	v_lshrrev_b32_e32 v5, 5, v173
	s_add_u32 s30, s95, s4
	v_and_b32_e32 v172, 31, v4
	s_addc_u32 s31, s22, s5
	v_lshlrev_b32_e32 v0, 4, v5
	v_lshl_add_u64 v[2:3], s[30:31], 0, v[0:1]
	v_lshl_or_b32 v0, s33, 6, v172
	v_lshlrev_b64 v[6:7], 10, v[0:1]
	v_or_b32_e32 v162, 32, v0
	v_mov_b32_e32 v163, v1
	v_lshl_add_u64 v[18:19], v[2:3], 0, v[6:7]
	v_lshlrev_b64 v[6:7], 10, v[162:163]
	s_waitcnt lgkmcnt(0)
	s_barrier
	v_lshl_add_u64 v[2:3], v[2:3], 0, v[6:7]
	global_load_dwordx4 v[6:9], v[18:19], off
	global_load_dwordx4 v[10:13], v[18:19], off offset:32
	global_load_dwordx4 v[14:17], v[18:19], off offset:64
	s_nop 0
	global_load_dwordx4 v[18:21], v[18:19], off offset:96
	s_nop 0
	global_load_dwordx4 v[22:25], v[2:3], off
	global_load_dwordx4 v[26:29], v[2:3], off offset:32
	global_load_dwordx4 v[30:33], v[2:3], off offset:64
	global_load_dwordx4 v[34:37], v[2:3], off offset:96
	s_mulk_i32 s10, 0x1bf0
	v_lshlrev_b32_e32 v38, 4, v173
	s_add_i32 s10, s8, s10
	v_and_b32_e32 v3, 32, v4
	v_add_u32_e32 v174, s10, v38
	s_lshl_b32 s10, s11, 16
	v_lshlrev_b32_e32 v2, 10, v172
	v_lshrrev_b32_e32 v3, 1, v3
	v_or3_b32 v2, s10, v2, v3
	s_lshl_b64 s[10:11], s[76:77], 1
	s_add_u32 s10, s10, s4
	v_mov_b32_e32 v3, v1
	s_addc_u32 s11, s11, s5
	v_lshl_add_u64 v[2:3], s[10:11], 0, v[2:3]
	s_mul_hi_u32 s10, s9, 0x2222223
	s_mul_hi_u32 s11, s10, 0x780000
	s_mul_i32 s30, s10, 0x780000
	v_subrev_co_u32_e32 v166, vcc, s30, v2
	v_mov_b32_e32 v2, s11
	s_lshl_b32 s9, s9, 13
	v_subb_co_u32_e32 v167, vcc, v3, v2, vcc
	s_add_u32 s2, s2, s9
	v_lshlrev_b32_e32 v2, 4, v172
	v_lshlrev_b32_e32 v3, 10, v5
	v_or3_b32 v2, v3, v2, s2
	s_addc_u32 s3, s3, 0
	v_or_b32_e32 v3, 0x200, v2
	s_mul_i32 s10, s10, 0xf0000
	v_mov_b32_e32 v4, s3
	v_subrev_co_u32_e32 v168, vcc, s10, v3
	v_lshlrev_b32_e32 v165, 2, v5
	s_nop 0
	v_subbrev_co_u32_e32 v169, vcc, 0, v4, vcc
	v_subrev_co_u32_e32 v170, vcc, s10, v2
	v_sub_u32_e32 v2, v172, v165
	s_nop 0
	v_subbrev_co_u32_e32 v171, vcc, 0, v4, vcc
	v_add_u32_e32 v177, 0x220, v2
	v_mov_b32_e32 v2, v1
	v_mov_b32_e32 v3, v1
	v_mov_b32_e32 v4, v1
	v_mov_b32_e32 v5, v1
	v_mov_b32_e32 v175, 0
	v_mov_b32_e32 v189, 0xf149f2ca
	s_mov_b32 s9, -1
	v_mov_b32_e32 v199, 0xf149f2ca
	v_mov_b32_e32 v176, 0
	v_readfirstlane_b32 s98, v252
	v_mbcnt_lo_u32_b32 v249, -1, 0
	v_mbcnt_hi_u32_b32 v249, -1, v249
	s_lshr_b32 s101, s98, 6
	s_lshl_b32 s98, s101, 13
	s_add_i32 s98, s98, 0x14000
	s_add_i32 s99, s98, 0x1c00
	s_mov_b32 s100, 0x1000
	s_cmp_eq_u32 s101, 7
	s_cselect_b32 s99, 0x3000, s99
	s_cselect_b32 s100, 0xfffe0400, s100
	v_and_b32_e32 v246, 31, v249
	v_lshrrev_b32_e32 v247, 5, v249
	v_bfe_u32 v248, v249, 1, 3
	v_lshl_add_u32 v250, v246, 7, s98
	v_xor_b32_e32 v241, v247, v248
	v_lshl_add_u32 v241, v241, 4, v250
	v_or_b32_e32 v242, 2, v247
	v_xor_b32_e32 v242, v242, v248
	v_lshl_add_u32 v242, v242, 4, v250
	v_or_b32_e32 v243, 4, v247
	v_xor_b32_e32 v243, v243, v248
	v_lshl_add_u32 v243, v243, 4, v250
	v_or_b32_e32 v244, 6, v247
	v_xor_b32_e32 v244, v244, v248
	v_lshl_add_u32 v244, v244, 4, v250
	v_mov_b32_e32 v245, 0x1000
	v_mov_b32_e32 v251, s100
	v_cmp_lt_u32_e32 vcc, 23, v246
	s_nop 1
	v_cndmask_b32_e32 v245, v245, v251, vcc
	v_add_u32_e32 v248, v244, v245
	v_add_u32_e32 v247, v243, v245
	v_add_u32_e32 v246, v242, v245
	v_add_u32_e32 v245, v241, v245
	v_lshrrev_b32_e32 v250, 3, v249
	v_lshlrev_b32_e32 v250, 10, v250
	v_and_b32_e32 v251, 7, v249
	v_lshrrev_b32_e32 v142, 4, v249
	v_xor_b32_e32 v251, v251, v142
	v_lshl_add_u32 v142, v251, 4, v250
	v_xor_b32_e32 v251, 4, v251
	v_lshl_add_u32 v250, v251, 4, v250
	v_add_u32_e32 v250, 0x2000, v250
	v_readfirstlane_b32 s100, v166
	v_readfirstlane_b32 s101, v167
	s_nop 0
	s_add_u32 s100, s100, s86
	s_addc_u32 s101, s101, s87
	s_add_u32 s100, s100, 0x85ee200
	s_addc_u32 s101, s101, 0
	v_mov_b32_e32 v143, 0
	v_mov_b32_e32 v251, 0
	v_lshl_add_u64 v[166:167], s[100:101], 0, v[142:143]
	v_lshl_add_u64 v[250:251], s[100:101], 0, v[250:251]
	s_mov_b64 s[100:101], 0x4000
	s_mov_b32 m0, s98
	s_nop 0
	global_load_lds_dwordx4 v[166:167], off
	s_add_i32 m0, s98, 0x400
	s_nop 0
	global_load_lds_dwordx4 v[250:251], off
	v_lshl_add_u64 v[142:143], v[166:167], 0, s[100:101]
	s_add_i32 m0, s98, 0x800
	s_nop 0
	global_load_lds_dwordx4 v[142:143], off
	v_lshl_add_u64 v[144:145], v[250:251], 0, s[100:101]
	s_add_i32 m0, s98, 0xc00
	s_nop 0
	global_load_lds_dwordx4 v[144:145], off
	v_lshl_add_u64 v[142:143], v[142:143], 0, s[100:101]
	s_add_i32 m0, s98, 0x1000
	s_nop 0
	global_load_lds_dwordx4 v[142:143], off
	v_lshl_add_u64 v[144:145], v[144:145], 0, s[100:101]
	s_add_i32 m0, s98, 0x1400
	s_nop 0
	global_load_lds_dwordx4 v[144:145], off
	v_lshl_add_u64 v[142:143], v[142:143], 0, s[100:101]
	s_add_i32 m0, s98, 0x1800
	s_nop 0
	global_load_lds_dwordx4 v[142:143], off
	v_lshl_add_u64 v[144:145], v[144:145], 0, s[100:101]
	s_mov_b32 m0, s99
	s_nop 0
	global_load_lds_dwordx4 v[144:145], off
	s_waitcnt vmcnt(7)
	s_waitcnt vmcnt(6)
	s_waitcnt vmcnt(5)
	s_waitcnt vmcnt(4)
	s_waitcnt vmcnt(3)
	s_waitcnt vmcnt(2)
	s_waitcnt vmcnt(1)
	s_waitcnt vmcnt(0)
	ds_write_b128 v174, v[6:9] offset:16384
	ds_write_b128 v174, v[10:13] offset:17408
	ds_write_b128 v174, v[14:17] offset:18432
	ds_write_b128 v174, v[18:21] offset:19456
	ds_write_b128 v174, v[22:25] offset:20480
	ds_write_b128 v174, v[26:29] offset:21504
	ds_write_b128 v174, v[30:33] offset:22528
	ds_write_b128 v174, v[34:37] offset:23552
	v_mov_b32_e32 v16, v1
	v_mov_b32_e32 v17, v1
	v_mov_b32_e32 v6, v1
	v_mov_b32_e32 v7, v1
	v_mov_b32_e32 v8, v1
	v_mov_b32_e32 v9, v1
	v_mov_b32_e32 v10, v1
	v_mov_b32_e32 v11, v1
	v_mov_b32_e32 v12, v1
	v_mov_b32_e32 v13, v1
	v_mov_b32_e32 v14, v1
	v_mov_b32_e32 v15, v1
	v_mov_b64_e32 v[48:49], v[16:17]
	v_mov_b64_e32 v[32:33], v[16:17]
	v_mov_b64_e32 v[64:65], v[16:17]
	v_mov_b64_e32 v[46:47], v[14:15]
	v_mov_b64_e32 v[44:45], v[12:13]
	v_mov_b64_e32 v[42:43], v[10:11]
	v_mov_b64_e32 v[40:41], v[8:9]
	v_mov_b64_e32 v[38:39], v[6:7]
	v_mov_b64_e32 v[36:37], v[4:5]
	v_mov_b64_e32 v[34:35], v[2:3]
	v_mov_b64_e32 v[30:31], v[14:15]
	v_mov_b64_e32 v[28:29], v[12:13]
	v_mov_b64_e32 v[26:27], v[10:11]
	v_mov_b64_e32 v[24:25], v[8:9]
	v_mov_b64_e32 v[22:23], v[6:7]
	v_mov_b64_e32 v[20:21], v[4:5]
	v_mov_b64_e32 v[18:19], v[2:3]
	v_mov_b64_e32 v[62:63], v[14:15]
	v_mov_b64_e32 v[60:61], v[12:13]
	v_mov_b64_e32 v[58:59], v[10:11]
	v_mov_b64_e32 v[56:57], v[8:9]
	v_mov_b64_e32 v[54:55], v[6:7]
	v_mov_b64_e32 v[52:53], v[4:5]
	v_mov_b64_e32 v[50:51], v[2:3]
	v_mov_b32_e32 v216, 0x3e38aa3b
	v_mov_b32_e32 v217, 0x3e38aa3b

.Lattn_near_p:
	s_waitcnt vmcnt(8)
	v_subrev_u32_e32 v188, 64, v177
	v_xor_b32_e32 v232, 32, v179
	v_lshlrev_b32_e32 v232, 2, v232
	v_max3_f32 v231, v98, v99, v100
	v_max3_f32 v231, v231, v101, v102
	v_max3_f32 v231, v231, v103, v104
	v_max3_f32 v231, v231, v105, v106
	v_max3_f32 v231, v231, v107, v108
	v_max3_f32 v231, v231, v109, v110
	v_max3_f32 v231, v231, v111, v112
	v_max3_f32 v231, v231, v113, v114
	v_max3_f32 v231, v231, v115, v116
	v_max3_f32 v231, v231, v117, v118
	v_max3_f32 v231, v231, v119, v120
	v_max3_f32 v231, v231, v121, v122
	v_max3_f32 v231, v231, v123, v124
	v_max3_f32 v231, v231, v125, v126
	v_max3_f32 v231, v231, v127, v128
	v_max_f32_e32 v231, v231, v129
	s_waitcnt lgkmcnt(0)
	v_fma_f32 v231, v231, v216, v190
	ds_bpermute_b32 v233, v232, v231
	v_max3_f32 v234, v66, v67, v68
	v_max3_f32 v234, v234, v69, v70
	v_max3_f32 v234, v234, v71, v72
	v_max3_f32 v234, v234, v73, v74
	v_max3_f32 v234, v234, v75, v76
	v_max3_f32 v234, v234, v77, v78
	v_max3_f32 v234, v234, v79, v80
	v_max3_f32 v234, v234, v81, v82
	v_max3_f32 v234, v234, v83, v84
	v_max3_f32 v234, v234, v85, v86
	v_max3_f32 v234, v234, v87, v88
	v_max3_f32 v234, v234, v89, v90
	v_max3_f32 v234, v234, v91, v92
	v_max3_f32 v234, v234, v93, v94
	v_max3_f32 v234, v234, v95, v96
	v_max_f32_e32 v234, v234, v97
	v_fma_f32 v234, v234, v216, v190
	ds_bpermute_b32 v235, v232, v234
	s_waitcnt lgkmcnt(1)
	v_max3_f32 v236, v199, v231, v233
	v_sub_f32_e32 v226, v199, v236
	v_sub_f32_e32 v238, v190, v236
	v_sub_f32_e32 v239, v190, v236
	v_exp_f32_e32 v226, v226
	v_pk_fma_f32 v[98:99], v[98:99], v[216:217], v[238:239]
	v_pk_fma_f32 v[100:101], v[100:101], v[216:217], v[238:239]
	v_pk_fma_f32 v[102:103], v[102:103], v[216:217], v[238:239]
	v_pk_fma_f32 v[104:105], v[104:105], v[216:217], v[238:239]
	v_pk_fma_f32 v[106:107], v[106:107], v[216:217], v[238:239]
	v_pk_fma_f32 v[108:109], v[108:109], v[216:217], v[238:239]
	v_pk_fma_f32 v[110:111], v[110:111], v[216:217], v[238:239]
	v_pk_fma_f32 v[112:113], v[112:113], v[216:217], v[238:239]
	v_pk_fma_f32 v[114:115], v[114:115], v[216:217], v[238:239]
	v_pk_fma_f32 v[116:117], v[116:117], v[216:217], v[238:239]
	v_pk_fma_f32 v[118:119], v[118:119], v[216:217], v[238:239]
	v_pk_fma_f32 v[120:121], v[120:121], v[216:217], v[238:239]
	v_pk_fma_f32 v[122:123], v[122:123], v[216:217], v[238:239]
	v_pk_fma_f32 v[124:125], v[124:125], v[216:217], v[238:239]
	v_pk_fma_f32 v[126:127], v[126:127], v[216:217], v[238:239]
	v_pk_fma_f32 v[128:129], v[128:129], v[216:217], v[238:239]
	v_exp_f32_e32 v98, v98
	v_exp_f32_e32 v99, v99
	v_exp_f32_e32 v100, v100
	v_exp_f32_e32 v101, v101
	v_exp_f32_e32 v102, v102
	v_exp_f32_e32 v103, v103
	v_exp_f32_e32 v104, v104
	v_exp_f32_e32 v105, v105
	v_exp_f32_e32 v106, v106
	v_exp_f32_e32 v107, v107
	v_exp_f32_e32 v108, v108
	v_exp_f32_e32 v109, v109
	v_exp_f32_e32 v110, v110
	v_exp_f32_e32 v111, v111
	v_exp_f32_e32 v112, v112
	v_exp_f32_e32 v113, v113
	v_exp_f32_e32 v114, v114
	v_exp_f32_e32 v115, v115
	v_exp_f32_e32 v116, v116
	v_exp_f32_e32 v117, v117
	v_exp_f32_e32 v118, v118
	v_exp_f32_e32 v119, v119
	v_exp_f32_e32 v120, v120
	v_exp_f32_e32 v121, v121
	v_exp_f32_e32 v122, v122
	v_exp_f32_e32 v123, v123
	v_exp_f32_e32 v124, v124
	v_exp_f32_e32 v125, v125
	v_exp_f32_e32 v126, v126
	v_exp_f32_e32 v127, v127
	v_exp_f32_e32 v128, v128
	v_exp_f32_e32 v129, v129
	s_waitcnt lgkmcnt(0)
	v_max3_f32 v218, v189, v234, v235
	v_sub_f32_e32 v228, v189, v218
	v_sub_f32_e32 v202, v190, v218
	v_sub_f32_e32 v203, v190, v218
	v_exp_f32_e32 v228, v228
	v_pk_fma_f32 v[66:67], v[66:67], v[216:217], v[202:203]
	v_pk_fma_f32 v[68:69], v[68:69], v[216:217], v[202:203]
	v_pk_fma_f32 v[70:71], v[70:71], v[216:217], v[202:203]
	v_pk_fma_f32 v[72:73], v[72:73], v[216:217], v[202:203]
	v_pk_fma_f32 v[74:75], v[74:75], v[216:217], v[202:203]
	v_pk_fma_f32 v[76:77], v[76:77], v[216:217], v[202:203]
	v_pk_fma_f32 v[78:79], v[78:79], v[216:217], v[202:203]
	v_pk_fma_f32 v[80:81], v[80:81], v[216:217], v[202:203]
	v_pk_fma_f32 v[82:83], v[82:83], v[216:217], v[202:203]
	v_pk_fma_f32 v[84:85], v[84:85], v[216:217], v[202:203]
	v_pk_fma_f32 v[86:87], v[86:87], v[216:217], v[202:203]
	v_pk_fma_f32 v[88:89], v[88:89], v[216:217], v[202:203]
	v_pk_fma_f32 v[90:91], v[90:91], v[216:217], v[202:203]
	v_pk_fma_f32 v[92:93], v[92:93], v[216:217], v[202:203]
	v_pk_fma_f32 v[94:95], v[94:95], v[216:217], v[202:203]
	v_pk_fma_f32 v[96:97], v[96:97], v[216:217], v[202:203]
	v_exp_f32_e32 v66, v66
	v_exp_f32_e32 v67, v67
	v_exp_f32_e32 v68, v68
	v_exp_f32_e32 v69, v69
	v_exp_f32_e32 v70, v70
	v_exp_f32_e32 v71, v71
	v_exp_f32_e32 v72, v72
	v_exp_f32_e32 v73, v73
	v_exp_f32_e32 v74, v74
	v_exp_f32_e32 v75, v75
	v_exp_f32_e32 v76, v76
	v_exp_f32_e32 v77, v77
	v_exp_f32_e32 v78, v78
	v_exp_f32_e32 v79, v79
	v_exp_f32_e32 v80, v80
	v_exp_f32_e32 v81, v81
	v_exp_f32_e32 v82, v82
	v_exp_f32_e32 v83, v83
	v_exp_f32_e32 v84, v84
	v_exp_f32_e32 v85, v85
	v_exp_f32_e32 v86, v86
	v_exp_f32_e32 v87, v87
	v_exp_f32_e32 v88, v88
	v_exp_f32_e32 v89, v89
	v_exp_f32_e32 v90, v90
	v_exp_f32_e32 v91, v91
	v_exp_f32_e32 v92, v92
	v_exp_f32_e32 v93, v93
	v_exp_f32_e32 v94, v94
	v_exp_f32_e32 v95, v95
	v_exp_f32_e32 v96, v96
	v_exp_f32_e32 v97, v97
	v_pk_add_f32 v[212:213], v[98:99], v[100:101]
	v_pk_add_f32 v[214:215], v[102:103], v[104:105]
	v_pk_add_f32 v[212:213], v[212:213], v[106:107]
	v_pk_add_f32 v[214:215], v[214:215], v[108:109]
	v_pk_add_f32 v[212:213], v[212:213], v[110:111]
	v_pk_add_f32 v[214:215], v[214:215], v[112:113]
	v_pk_add_f32 v[212:213], v[212:213], v[114:115]
	v_pk_add_f32 v[214:215], v[214:215], v[116:117]
	v_pk_add_f32 v[212:213], v[212:213], v[118:119]
	v_pk_add_f32 v[214:215], v[214:215], v[120:121]
	v_pk_add_f32 v[212:213], v[212:213], v[122:123]
	v_pk_add_f32 v[214:215], v[214:215], v[124:125]
	v_pk_add_f32 v[212:213], v[212:213], v[126:127]
	v_pk_add_f32 v[214:215], v[214:215], v[128:129]
	v_pk_add_f32 v[212:213], v[212:213], v[214:215]
	v_add_f32_e32 v210, v212, v213
	ds_bpermute_b32 v211, v232, v210
	v_pk_add_f32 v[220:221], v[66:67], v[68:69]
	v_pk_add_f32 v[222:223], v[70:71], v[72:73]
	v_pk_add_f32 v[220:221], v[220:221], v[74:75]
	v_pk_add_f32 v[222:223], v[222:223], v[76:77]
	v_pk_add_f32 v[220:221], v[220:221], v[78:79]
	v_pk_add_f32 v[222:223], v[222:223], v[80:81]
	v_pk_add_f32 v[220:221], v[220:221], v[82:83]
	v_pk_add_f32 v[222:223], v[222:223], v[84:85]
	v_pk_add_f32 v[220:221], v[220:221], v[86:87]
	v_pk_add_f32 v[222:223], v[222:223], v[88:89]
	v_pk_add_f32 v[220:221], v[220:221], v[90:91]
	v_pk_add_f32 v[222:223], v[222:223], v[92:93]
	v_pk_add_f32 v[220:221], v[220:221], v[94:95]
	v_pk_add_f32 v[222:223], v[222:223], v[96:97]
	v_pk_add_f32 v[220:221], v[220:221], v[222:223]
	v_add_f32_e32 v224, v220, v221
	ds_bpermute_b32 v225, v232, v224
	v_cmp_neq_f32_e32 vcc, 1.0, v226
	s_cbranch_vccz .Lattn_near_p_sa
	v_mov_b32_e32 v227, v226
	v_pk_mul_f32 v[64:65], v[64:65], v[226:227]
	v_pk_mul_f32 v[62:63], v[62:63], v[226:227]
	v_pk_mul_f32 v[60:61], v[60:61], v[226:227]
	v_pk_mul_f32 v[58:59], v[58:59], v[226:227]
	v_pk_mul_f32 v[56:57], v[56:57], v[226:227]
	v_pk_mul_f32 v[54:55], v[54:55], v[226:227]
	v_pk_mul_f32 v[52:53], v[52:53], v[226:227]
	v_pk_mul_f32 v[50:51], v[50:51], v[226:227]
	v_pk_mul_f32 v[48:49], v[48:49], v[226:227]
	v_pk_mul_f32 v[46:47], v[46:47], v[226:227]
	v_pk_mul_f32 v[44:45], v[44:45], v[226:227]
	v_pk_mul_f32 v[42:43], v[42:43], v[226:227]
	v_pk_mul_f32 v[40:41], v[40:41], v[226:227]
	v_pk_mul_f32 v[38:39], v[38:39], v[226:227]
	v_pk_mul_f32 v[36:37], v[36:37], v[226:227]
	v_pk_mul_f32 v[34:35], v[34:35], v[226:227]
.Lattn_near_p_sa:
	v_cmp_neq_f32_e32 vcc, 1.0, v228
	s_cbranch_vccz .Lattn_near_p_sb
	v_mov_b32_e32 v229, v228
	v_pk_mul_f32 v[32:33], v[32:33], v[228:229]
	v_pk_mul_f32 v[30:31], v[30:31], v[228:229]
	v_pk_mul_f32 v[28:29], v[28:29], v[228:229]
	v_pk_mul_f32 v[26:27], v[26:27], v[228:229]
	v_pk_mul_f32 v[24:25], v[24:25], v[228:229]
	v_pk_mul_f32 v[22:23], v[22:23], v[228:229]
	v_pk_mul_f32 v[20:21], v[20:21], v[228:229]
	v_pk_mul_f32 v[18:19], v[18:19], v[228:229]
	v_pk_mul_f32 v[16:17], v[16:17], v[228:229]
	v_pk_mul_f32 v[14:15], v[14:15], v[228:229]
	v_pk_mul_f32 v[12:13], v[12:13], v[228:229]
	v_pk_mul_f32 v[10:11], v[10:11], v[228:229]
	v_pk_mul_f32 v[8:9], v[8:9], v[228:229]
	v_pk_mul_f32 v[6:7], v[6:7], v[228:229]
	v_pk_mul_f32 v[4:5], v[4:5], v[228:229]
	v_pk_mul_f32 v[2:3], v[2:3], v[228:229]
